# v46: SWA score stage keeps 8 K-fragment LDS reads in flight (8 register quads) instead of 1-2 (MFMA/LDS interleave)
# speedup vs baseline: 1.0018x; 1.0018x over previous
; #define LAS __attribute__((address_space(3)))
; template <class T> __device__ __forceinline__ LAS T* opq(LAS T* p) { unsigned a = __builtin_bit_cast(unsigned, p); asm volatile("" : "+v"(a)); return __builtin_bit_cast(LAS T*, a); }
; #define MFMA32(a, b, c) __builtin_amdgcn_mfma_f32_32x32x16_bf16((a), (b), (c), 0, 0, 0)
; __device__ __forceinline__ void phase(LAS unsigned char* lds, int bx, int G, bf16_t* AB, bf16_t* dummy, const bf16_t* SKV, const float* cache_k, const float* cache_v, const float* sinks, const float* rel_bias) {
;     ...
;         const bool active = !samp || w < 2;
;         int g = 0, tq = 0;
;         if (!samp) { g = w >> 1; tq = 32 * (w & 1) + r; }
;         else { const int ir = (32 * w + r) & 63; g = ir >> 4; tq = ir & 15; }
;         bf16x8 qf[4];
; #pragma unroll
;         for (int s = 0; s < 4; ++s) qf[s] = qn[s];
;         if (k + 1 < cnt) { const Item tn = decode(item_of(k + 1)); fetch(tn, SKV, cache_k, cache_v, kw, vw); SWA_QFETCH(tn); }
;         if (active) {
;             const unsigned vm = (kvmax >= 192 ? 0xffffffu : ((1u << (kvmax >> 3)) - 1u)) & ~((1u << (kvmin >> 3)) - 1u);
;             f32x16 sc[6];
;             {
;                 const LAS bf16_t* krp = opq(Ks + r * KST + 8 * h);
; #pragma unroll
;                 for (int blk = 0; blk < 6; ++blk) {
;                     f32x16 a;
; #pragma unroll
;                     for (int i = 0; i < 16; ++i) a[i] = ((vm >> (4 * blk + (i >> 2))) & 1u) ? 0.f : -1e30f;
; #pragma unroll
;                     for (int s = 0; s < 4; ++s) { const bf16x8 kf = *(const LAS bf16x8*)(krp + (32 * blk) * KST + 16 * s); a = MFMA32(kf, qf[s], a); }
;                     sc[blk] = a;
;                 }
;             }
.LBB0_1187:
	s_and_b64 s[6:7], s[4:5], s[14:15]
	s_and_b64 vcc, exec, s[6:7]
	s_cbranch_vccnz .LBB0_1131
	s_lshr_b32 s6, s34, 3
	s_lshl_b32 s6, -1, s6
	s_not_b32 s10, s6
	s_and_b64 s[6:7], exec, s[4:5]
	s_cselect_b32 s6, s10, 0xffffff
	s_lshr_b32 s7, s35, 3
	v_mov_b32_e32 v161, v184
	s_lshl_b32 s7, -1, s7
	ds_read_b128 v[204:207], v161
	ds_read_b128 v[208:211], v161 offset:32
	ds_read_b128 v[212:215], v161 offset:64
	ds_read_b128 v[216:219], v161 offset:96
	ds_read_b128 v[220:223], v161 offset:4608
	ds_read_b128 v[224:227], v161 offset:4640
	ds_read_b128 v[228:231], v161 offset:4672
	ds_read_b128 v[232:235], v161 offset:4704
	s_and_b32 s6, s7, s6
	s_bitcmp0_b32 s6, 0
	s_cselect_b64 vcc, -1, 0
	s_bitcmp0_b32 s6, 1
	v_cndmask_b32_e32 v82, 0, v190, vcc
	s_cselect_b64 vcc, -1, 0
	s_bitcmp0_b32 s6, 2
	v_cndmask_b32_e32 v86, 0, v190, vcc
	s_cselect_b64 vcc, -1, 0
	s_bitcmp0_b32 s6, 3
	v_cndmask_b32_e32 v90, 0, v190, vcc
	s_cselect_b64 vcc, -1, 0
	v_cndmask_b32_e32 v94, 0, v190, vcc
	v_mov_b32_e32 v83, v82
	v_mov_b32_e32 v84, v82
	v_mov_b32_e32 v85, v82
	v_mov_b32_e32 v87, v86
	v_mov_b32_e32 v88, v86
	v_mov_b32_e32 v89, v86
	v_mov_b32_e32 v91, v90
	v_mov_b32_e32 v92, v90
	v_mov_b32_e32 v93, v90
	v_mov_b32_e32 v95, v94
	v_mov_b32_e32 v96, v94
	v_mov_b32_e32 v97, v94
	s_bitcmp0_b32 s6, 4
	s_cselect_b64 vcc, -1, 0
	s_waitcnt lgkmcnt(7)
	v_mfma_f32_32x32x16_bf16 v[82:97], v[204:207], v[150:153], v[82:97]
	ds_read_b128 v[204:207], v161 offset:9216
	s_bitcmp0_b32 s6, 5
	v_cndmask_b32_e32 v66, 0, v190, vcc
	s_cselect_b64 vcc, -1, 0
	s_bitcmp0_b32 s6, 6
	v_cndmask_b32_e32 v70, 0, v190, vcc
	s_cselect_b64 vcc, -1, 0
	s_bitcmp0_b32 s6, 7
	s_waitcnt lgkmcnt(7)
	v_mfma_f32_32x32x16_bf16 v[82:97], v[208:211], v[146:149], v[82:97]
	ds_read_b128 v[208:211], v161 offset:9248
	v_cndmask_b32_e32 v74, 0, v190, vcc
	s_cselect_b64 vcc, -1, 0
	v_cndmask_b32_e32 v78, 0, v190, vcc
	v_mov_b32_e32 v67, v66
	v_mov_b32_e32 v68, v66
	v_mov_b32_e32 v69, v66
	s_waitcnt lgkmcnt(7)
	v_mfma_f32_32x32x16_bf16 v[82:97], v[212:215], v[142:145], v[82:97]
	ds_read_b128 v[212:215], v161 offset:9280
	v_mov_b32_e32 v71, v70
	v_mov_b32_e32 v72, v70
	v_mov_b32_e32 v73, v70
	v_mov_b32_e32 v75, v74
	v_mov_b32_e32 v76, v74
	v_mov_b32_e32 v77, v74
	s_waitcnt lgkmcnt(7)
	v_mfma_f32_32x32x16_bf16 v[82:97], v[216:219], v[138:141], v[82:97]
	ds_read_b128 v[216:219], v161 offset:9312
	v_mov_b32_e32 v79, v78
	v_mov_b32_e32 v80, v78
	v_mov_b32_e32 v81, v78
	s_bitcmp0_b32 s6, 8
	s_cselect_b64 vcc, -1, 0
	s_bitcmp0_b32 s6, 9
	s_waitcnt lgkmcnt(7)
	v_mfma_f32_32x32x16_bf16 v[66:81], v[220:223], v[150:153], v[66:81]
	ds_read_b128 v[220:223], v161 offset:13824
	v_cndmask_b32_e32 v50, 0, v190, vcc
	s_cselect_b64 vcc, -1, 0
	s_bitcmp0_b32 s6, 10
	v_cndmask_b32_e32 v54, 0, v190, vcc
	s_cselect_b64 vcc, -1, 0
	s_bitcmp0_b32 s6, 11
	v_cndmask_b32_e32 v58, 0, v190, vcc
	s_waitcnt lgkmcnt(7)
	v_mfma_f32_32x32x16_bf16 v[66:81], v[224:227], v[146:149], v[66:81]
	ds_read_b128 v[224:227], v161 offset:13856
	s_cselect_b64 vcc, -1, 0
	v_cndmask_b32_e32 v62, 0, v190, vcc
	v_mov_b32_e32 v51, v50
	v_mov_b32_e32 v52, v50
	v_mov_b32_e32 v53, v50
	v_mov_b32_e32 v55, v54
	s_waitcnt lgkmcnt(7)
	v_mfma_f32_32x32x16_bf16 v[66:81], v[228:231], v[142:145], v[66:81]
	ds_read_b128 v[228:231], v161 offset:13888
	v_mov_b32_e32 v56, v54
	v_mov_b32_e32 v57, v54
	v_mov_b32_e32 v59, v58
	v_mov_b32_e32 v60, v58
	v_mov_b32_e32 v61, v58
	v_mov_b32_e32 v63, v62
	s_waitcnt lgkmcnt(7)
	v_mfma_f32_32x32x16_bf16 v[66:81], v[232:235], v[138:141], v[66:81]
	ds_read_b128 v[232:235], v161 offset:13920
	v_mov_b32_e32 v64, v62
	v_mov_b32_e32 v65, v62
	s_bitcmp0_b32 s6, 12
	s_cselect_b64 vcc, -1, 0
	s_bitcmp0_b32 s6, 13
	v_cndmask_b32_e32 v34, 0, v190, vcc
	s_waitcnt lgkmcnt(7)
	v_mfma_f32_32x32x16_bf16 v[50:65], v[204:207], v[150:153], v[50:65]
	ds_read_b128 v[204:207], v161 offset:18432
	s_cselect_b64 vcc, -1, 0
	s_bitcmp0_b32 s6, 14
	v_cndmask_b32_e32 v38, 0, v190, vcc
	s_cselect_b64 vcc, -1, 0
	s_bitcmp0_b32 s6, 15
	v_cndmask_b32_e32 v42, 0, v190, vcc
	s_cselect_b64 vcc, -1, 0
	s_waitcnt lgkmcnt(7)
	v_mfma_f32_32x32x16_bf16 v[50:65], v[208:211], v[146:149], v[50:65]
	ds_read_b128 v[208:211], v161 offset:18464
	v_cndmask_b32_e32 v46, 0, v190, vcc
	v_mov_b32_e32 v35, v34
	v_mov_b32_e32 v36, v34
	v_mov_b32_e32 v37, v34
	v_mov_b32_e32 v39, v38
	v_mov_b32_e32 v40, v38
	s_waitcnt lgkmcnt(7)
	v_mfma_f32_32x32x16_bf16 v[50:65], v[212:215], v[142:145], v[50:65]
	v_mov_b32_e32 v41, v38
	v_mov_b32_e32 v43, v42
	v_mov_b32_e32 v44, v42
	v_mov_b32_e32 v45, v42
	v_mov_b32_e32 v47, v46
	v_mov_b32_e32 v48, v46
	s_waitcnt lgkmcnt(6)
	v_mfma_f32_32x32x16_bf16 v[50:65], v[216:219], v[138:141], v[50:65]
	v_mov_b32_e32 v49, v46
	s_bitcmp0_b32 s6, 16
	s_cselect_b64 vcc, -1, 0
	s_bitcmp0_b32 s6, 17
	v_cndmask_b32_e32 v18, 0, v190, vcc
	s_cselect_b64 vcc, -1, 0
	s_waitcnt lgkmcnt(5)
	v_mfma_f32_32x32x16_bf16 v[34:49], v[220:223], v[150:153], v[34:49]
	s_bitcmp0_b32 s6, 18
	v_cndmask_b32_e32 v22, 0, v190, vcc
	s_cselect_b64 vcc, -1, 0
	s_bitcmp0_b32 s6, 19
	v_cndmask_b32_e32 v26, 0, v190, vcc
	s_cselect_b64 vcc, -1, 0
	v_cndmask_b32_e32 v30, 0, v190, vcc
	s_waitcnt lgkmcnt(4)
	v_mfma_f32_32x32x16_bf16 v[34:49], v[224:227], v[146:149], v[34:49]
	v_mov_b32_e32 v19, v18
	v_mov_b32_e32 v20, v18
	v_mov_b32_e32 v21, v18
	v_mov_b32_e32 v23, v22
	v_mov_b32_e32 v24, v22
	v_mov_b32_e32 v25, v22
	s_waitcnt lgkmcnt(3)
	v_mfma_f32_32x32x16_bf16 v[34:49], v[228:231], v[142:145], v[34:49]
	v_mov_b32_e32 v27, v26
	v_mov_b32_e32 v28, v26
	v_mov_b32_e32 v29, v26
	v_mov_b32_e32 v31, v30
	v_mov_b32_e32 v32, v30
	v_mov_b32_e32 v33, v30
	s_waitcnt lgkmcnt(2)
; #define LAS __attribute__((address_space(3)))
; template <class T> __device__ __forceinline__ LAS T* opq(LAS T* p) { unsigned a = __builtin_bit_cast(unsigned, p); asm volatile("" : "+v"(a)); return __builtin_bit_cast(LAS T*, a); }
; #define MFMA32(a, b, c) __builtin_amdgcn_mfma_f32_32x32x16_bf16((a), (b), (c), 0, 0, 0)
; __device__ __forceinline__ void phase(LAS unsigned char* lds, int bx, int G, bf16_t* AB, bf16_t* dummy, const bf16_t* SKV, const float* cache_k, const float* cache_v, const float* sinks, const float* rel_bias) {
;     ...
;                     for (int s = 0; s < 4; ++s) { const bf16x8 kf = *(const LAS bf16x8*)(krp + (32 * blk) * KST + 16 * s); a = MFMA32(kf, qf[s], a); }
;                     sc[blk] = a;
;                 }
;             }
;             const float sink = tbl[g * 256 + 255];
;             const LAS float* tb = opq(tbl + g * 256 + 63 - tq + 4 * h);
;             typedef float f32x2 __attribute__((ext_vector_type(2)));
;             float mx = sink;
; #pragma unroll
;             for (int blk = 0; blk < 6; ++blk) {
; #pragma unroll
;                 for (int q4 = 0; q4 < 4; ++q4) {
;                     const LAS float* tp = tb + 32 * blk + 8 * q4;
;                     f32x2 a = (f32x2){sc[blk][4 * q4], sc[blk][4 * q4 + 1]} + (f32x2){tp[0], tp[1]};
;                     f32x2 b = (f32x2){sc[blk][4 * q4 + 2], sc[blk][4 * q4 + 3]} + (f32x2){tp[2], tp[3]};
;                     sc[blk][4 * q4] = a[0]; sc[blk][4 * q4 + 1] = a[1]; sc[blk][4 * q4 + 2] = b[0]; sc[blk][4 * q4 + 3] = b[1];
;                     mx = fmaxf(fmaxf(mx, a[0]), a[1]); mx = fmaxf(fmaxf(mx, b[0]), b[1]);
;                 }
;                 __builtin_amdgcn_sched_barrier(0);
;             }
;             mx = fmaxf(mx, __shfl_xor(mx, 32));
	v_mfma_f32_32x32x16_bf16 v[34:49], v[232:235], v[138:141], v[34:49]
	s_bitcmp0_b32 s6, 20
	s_cselect_b64 vcc, -1, 0
	s_bitcmp0_b32 s6, 21
	v_cndmask_b32_e64 v164, v180, v182, s[4:5]
	s_waitcnt lgkmcnt(1)
	v_mfma_f32_32x32x16_bf16 v[18:33], v[204:207], v[150:153], v[18:33]
	s_waitcnt lgkmcnt(0)
	v_mfma_f32_32x32x16_bf16 v[18:33], v[208:211], v[146:149], v[18:33]
	ds_read_b128 v[2:5], v161 offset:18496
	ds_read_b128 v[6:9], v161 offset:18528
	ds_read_b128 v[166:169], v161 offset:23040
	ds_read_b128 v[170:173], v161 offset:23072
	s_waitcnt lgkmcnt(3)
	v_mfma_f32_32x32x16_bf16 v[18:33], v[2:5], v[142:145], v[18:33]
	v_cndmask_b32_e32 v2, 0, v190, vcc
	s_cselect_b64 vcc, -1, 0
	s_bitcmp0_b32 s6, 22
	v_mov_b32_e32 v3, v2
	v_mov_b32_e32 v4, v2
	v_mov_b32_e32 v5, v2
	s_waitcnt lgkmcnt(2)
	v_mfma_f32_32x32x16_bf16 v[18:33], v[6:9], v[138:141], v[18:33]
	v_cndmask_b32_e32 v6, 0, v190, vcc
	s_cselect_b64 vcc, -1, 0
	s_bitcmp0_b32 s6, 23
	v_cndmask_b32_e32 v10, 0, v190, vcc
	s_cselect_b64 vcc, -1, 0
	v_cndmask_b32_e32 v14, 0, v190, vcc
	v_mov_b32_e32 v7, v6
	v_mov_b32_e32 v8, v6
	v_mov_b32_e32 v9, v6
	v_mov_b32_e32 v11, v10
	v_mov_b32_e32 v12, v10
	v_mov_b32_e32 v13, v10
	v_mov_b32_e32 v15, v14
	v_mov_b32_e32 v16, v14
	v_mov_b32_e32 v17, v14
	s_waitcnt lgkmcnt(1)
	s_nop 0
	v_mfma_f32_32x32x16_bf16 v[2:17], v[166:169], v[150:153], v[2:17]
	v_mov_b32_e32 v150, s19
	v_cndmask_b32_e64 v166, v150, v181, s[4:5]
	ds_read_b128 v[150:153], v161 offset:23136
	s_mov_b32 s4, 0xfcfc
	s_waitcnt lgkmcnt(1)
	v_mfma_f32_32x32x16_bf16 v[2:17], v[170:173], v[146:149], v[2:17]
	ds_read_b128 v[146:149], v161 offset:23104
	s_waitcnt lgkmcnt(0)
	v_mfma_f32_32x32x16_bf16 v[2:17], v[146:149], v[142:145], v[2:17]
	v_lshl_add_u32 v142, v166, 10, 0
	v_lshlrev_b32_e32 v143, 2, v164
	ds_read_b32 v161, v142 offset:65532
	v_sub_u32_e32 v142, v142, v143
	v_lshlrev_b32_e32 v143, 2, v185
	v_add3_u32 v164, v142, v143, s4
	ds_read2_b32 v[142:143], v164 offset1:1
	ds_read2_b32 v[144:145], v164 offset0:2 offset1:3
	ds_read2_b32 v[146:147], v164 offset0:8 offset1:9
	ds_read2_b32 v[148:149], v164 offset0:10 offset1:11
	v_mfma_f32_32x32x16_bf16 v[2:17], v[150:153], v[138:141], v[2:17]
	s_waitcnt lgkmcnt(3)
	v_add_f32_e64 v140, v82, v142
	v_add_f32_e64 v141, v83, v143
	s_waitcnt lgkmcnt(2)
	v_add_f32_e64 v138, v84, v144
	v_add_f32_e64 v139, v85, v145
	v_max3_f32 v82, v161, v140, v141
	v_max3_f32 v142, v82, v138, v139
	s_waitcnt lgkmcnt(1)
	v_pk_add_f32 v[84:85], v[86:87], v[146:147]
	s_waitcnt lgkmcnt(0)
	v_pk_add_f32 v[82:83], v[88:89], v[148:149]
	ds_read2_b32 v[86:87], v164 offset0:16 offset1:17
	ds_read2_b32 v[88:89], v164 offset0:18 offset1:19
	ds_read2_b32 v[144:145], v164 offset0:24 offset1:25
	ds_read2_b32 v[146:147], v164 offset0:26 offset1:27
	v_max3_f32 v142, v142, v84, v85
	v_max3_f32 v148, v142, v82, v83
	s_waitcnt lgkmcnt(3)
	v_pk_add_f32 v[142:143], v[90:91], v[86:87]
	s_waitcnt lgkmcnt(2)
	v_pk_add_f32 v[88:89], v[92:93], v[88:89]
	v_max3_f32 v86, v148, v142, v143
	v_max3_f32 v92, v86, v88, v89
	s_waitcnt lgkmcnt(1)
	v_pk_add_f32 v[90:91], v[94:95], v[144:145]
	s_waitcnt lgkmcnt(0)
	v_pk_add_f32 v[86:87], v[96:97], v[146:147]
	v_max3_f32 v92, v92, v90, v91
	v_max3_f32 v146, v92, v86, v87
	ds_read2_b32 v[92:93], v164 offset0:32 offset1:33
	ds_read2_b32 v[94:95], v164 offset0:34 offset1:35
	ds_read2_b32 v[96:97], v164 offset0:40 offset1:41
	ds_read2_b32 v[144:145], v164 offset0:42 offset1:43
	s_waitcnt lgkmcnt(3)
	v_pk_add_f32 v[92:93], v[66:67], v[92:93]
	s_waitcnt lgkmcnt(2)
	v_pk_add_f32 v[68:69], v[68:69], v[94:95]
	v_max3_f32 v66, v146, v92, v93
	v_max3_f32 v94, v66, v68, v69
	s_waitcnt lgkmcnt(1)
	v_pk_add_f32 v[70:71], v[70:71], v[96:97]
	s_waitcnt lgkmcnt(0)
	v_pk_add_f32 v[66:67], v[72:73], v[144:145]
	ds_read2_b32 v[72:73], v164 offset0:48 offset1:49
	ds_read2_b32 v[96:97], v164 offset0:50 offset1:51
	ds_read2_b32 v[144:145], v164 offset0:56 offset1:57
	ds_read2_b32 v[146:147], v164 offset0:58 offset1:59
	v_max3_f32 v94, v94, v70, v71
	v_max3_f32 v148, v94, v66, v67
	s_waitcnt lgkmcnt(3)
	v_pk_add_f32 v[94:95], v[74:75], v[72:73]
	s_waitcnt lgkmcnt(2)
	v_pk_add_f32 v[74:75], v[76:77], v[96:97]
	v_max3_f32 v72, v148, v94, v95
	v_max3_f32 v96, v72, v74, v75
	s_waitcnt lgkmcnt(1)
	v_pk_add_f32 v[76:77], v[78:79], v[144:145]
	s_waitcnt lgkmcnt(0)
	v_pk_add_f32 v[72:73], v[80:81], v[146:147]
	v_max3_f32 v78, v96, v76, v77
	v_max3_f32 v146, v78, v72, v73
	ds_read2_b32 v[78:79], v164 offset0:64 offset1:65
	ds_read2_b32 v[80:81], v164 offset0:66 offset1:67
	ds_read2_b32 v[96:97], v164 offset0:72 offset1:73
	ds_read2_b32 v[144:145], v164 offset0:74 offset1:75
	s_waitcnt lgkmcnt(3)
	v_pk_add_f32 v[50:51], v[50:51], v[78:79]
	s_waitcnt lgkmcnt(2)
	v_pk_add_f32 v[52:53], v[52:53], v[80:81]
	v_max3_f32 v78, v146, v50, v51
	v_max3_f32 v78, v78, v52, v53
	s_waitcnt lgkmcnt(1)
	v_pk_add_f32 v[54:55], v[54:55], v[96:97]
	s_waitcnt lgkmcnt(0)
	v_pk_add_f32 v[56:57], v[56:57], v[144:145]
	v_max3_f32 v96, v78, v54, v55
	ds_read2_b32 v[78:79], v164 offset0:80 offset1:81
	ds_read2_b32 v[80:81], v164 offset0:82 offset1:83
	v_max3_f32 v146, v96, v56, v57
	ds_read2_b32 v[96:97], v164 offset0:88 offset1:89
	ds_read2_b32 v[144:145], v164 offset0:90 offset1:91
	s_waitcnt lgkmcnt(3)
	v_pk_add_f32 v[58:59], v[58:59], v[78:79]
	s_waitcnt lgkmcnt(2)
	v_pk_add_f32 v[60:61], v[60:61], v[80:81]
	v_max3_f32 v78, v146, v58, v59
	v_max3_f32 v78, v78, v60, v61
	s_waitcnt lgkmcnt(1)
	v_pk_add_f32 v[62:63], v[62:63], v[96:97]
	s_waitcnt lgkmcnt(0)
; #define LAS __attribute__((address_space(3)))
; __device__ __forceinline__ void phase(LAS unsigned char* lds, int bx, int G, bf16_t* AB, bf16_t* dummy, const bf16_t* SKV, const float* cache_k, const float* cache_v, const float* sinks, const float* rel_bias) {
;     ...
;             for (int blk = 0; blk < 6; ++blk) {
; #pragma unroll
;                 for (int q4 = 0; q4 < 4; ++q4) {
;                     const LAS float* tp = tb + 32 * blk + 8 * q4;
;                     f32x2 a = (f32x2){sc[blk][4 * q4], sc[blk][4 * q4 + 1]} + (f32x2){tp[0], tp[1]};
;                     f32x2 b = (f32x2){sc[blk][4 * q4 + 2], sc[blk][4 * q4 + 3]} + (f32x2){tp[2], tp[3]};
;                     sc[blk][4 * q4] = a[0]; sc[blk][4 * q4 + 1] = a[1]; sc[blk][4 * q4 + 2] = b[0]; sc[blk][4 * q4 + 3] = b[1];
;                     mx = fmaxf(fmaxf(mx, a[0]), a[1]); mx = fmaxf(fmaxf(mx, b[0]), b[1]);
;                 }
;                 __builtin_amdgcn_sched_barrier(0);
;             }
;             mx = fmaxf(mx, __shfl_xor(mx, 32));
;             const f32x2 nm = (f32x2){-mx, -mx};
;             f32x2 l2 = (f32x2){0.f, 0.f};
; #pragma unroll
;             for (int blk = 0; blk < 6; ++blk)
; #pragma unroll
;                 for (int q2 = 0; q2 < 8; ++q2) {
;                     const f32x2 a = (f32x2){sc[blk][2 * q2], sc[blk][2 * q2 + 1]} + nm;
;                     const f32x2 pe = (f32x2){__builtin_amdgcn_exp2f(a[0]), __builtin_amdgcn_exp2f(a[1])};
;                     sc[blk][2 * q2] = pe[0]; sc[blk][2 * q2 + 1] = pe[1]; l2 += pe;
;                 }
;             float l = l2[0] + l2[1];
;             l += __shfl_xor(l, 32);
;             l += __builtin_amdgcn_exp2f(sink - mx);
	v_pk_add_f32 v[64:65], v[64:65], v[144:145]
	v_max3_f32 v78, v78, v62, v63
	v_max3_f32 v146, v78, v64, v65
	ds_read2_b32 v[78:79], v164 offset0:96 offset1:97
	ds_read2_b32 v[80:81], v164 offset0:98 offset1:99
	ds_read2_b32 v[96:97], v164 offset0:104 offset1:105
	ds_read2_b32 v[144:145], v164 offset0:106 offset1:107
	s_waitcnt lgkmcnt(3)
	v_pk_add_f32 v[34:35], v[34:35], v[78:79]
	s_waitcnt lgkmcnt(2)
	v_pk_add_f32 v[36:37], v[36:37], v[80:81]
	v_max3_f32 v78, v146, v34, v35
	v_max3_f32 v78, v78, v36, v37
	s_waitcnt lgkmcnt(1)
	v_pk_add_f32 v[38:39], v[38:39], v[96:97]
	s_waitcnt lgkmcnt(0)
	v_pk_add_f32 v[40:41], v[40:41], v[144:145]
	v_max3_f32 v96, v78, v38, v39
	ds_read2_b32 v[78:79], v164 offset0:112 offset1:113
	ds_read2_b32 v[80:81], v164 offset0:114 offset1:115
	v_max3_f32 v146, v96, v40, v41
	ds_read2_b32 v[96:97], v164 offset0:120 offset1:121
	ds_read2_b32 v[144:145], v164 offset0:122 offset1:123
	s_waitcnt lgkmcnt(3)
	v_pk_add_f32 v[42:43], v[42:43], v[78:79]
	s_waitcnt lgkmcnt(2)
	v_pk_add_f32 v[44:45], v[44:45], v[80:81]
	v_max3_f32 v78, v146, v42, v43
	v_max3_f32 v78, v78, v44, v45
	s_waitcnt lgkmcnt(1)
	v_pk_add_f32 v[46:47], v[46:47], v[96:97]
	s_waitcnt lgkmcnt(0)
	v_pk_add_f32 v[48:49], v[48:49], v[144:145]
	v_max3_f32 v78, v78, v46, v47
	v_max3_f32 v146, v78, v48, v49
	ds_read2_b32 v[78:79], v164 offset0:128 offset1:129
	ds_read2_b32 v[80:81], v164 offset0:130 offset1:131
	ds_read2_b32 v[96:97], v164 offset0:136 offset1:137
	ds_read2_b32 v[144:145], v164 offset0:138 offset1:139
	s_waitcnt lgkmcnt(3)
	v_pk_add_f32 v[18:19], v[18:19], v[78:79]
	s_waitcnt lgkmcnt(2)
	v_pk_add_f32 v[20:21], v[20:21], v[80:81]
	v_max3_f32 v78, v146, v18, v19
	v_max3_f32 v78, v78, v20, v21
	s_waitcnt lgkmcnt(1)
	v_pk_add_f32 v[22:23], v[22:23], v[96:97]
	s_waitcnt lgkmcnt(0)
	v_pk_add_f32 v[24:25], v[24:25], v[144:145]
	v_max3_f32 v96, v78, v22, v23
	ds_read2_b32 v[78:79], v164 offset0:144 offset1:145
	ds_read2_b32 v[80:81], v164 offset0:146 offset1:147
	v_max3_f32 v146, v96, v24, v25
	ds_read2_b32 v[96:97], v164 offset0:152 offset1:153
	ds_read2_b32 v[144:145], v164 offset0:154 offset1:155
	s_waitcnt lgkmcnt(3)
	v_pk_add_f32 v[26:27], v[26:27], v[78:79]
	s_waitcnt lgkmcnt(2)
	v_pk_add_f32 v[28:29], v[28:29], v[80:81]
	v_max3_f32 v78, v146, v26, v27
	v_max3_f32 v78, v78, v28, v29
	s_waitcnt lgkmcnt(1)
	v_pk_add_f32 v[30:31], v[30:31], v[96:97]
	s_waitcnt lgkmcnt(0)
	v_pk_add_f32 v[32:33], v[32:33], v[144:145]
	v_max3_f32 v78, v78, v30, v31
	v_max3_f32 v146, v78, v32, v33
	ds_read2_b32 v[78:79], v164 offset0:160 offset1:161
	ds_read2_b32 v[80:81], v164 offset0:162 offset1:163
	ds_read2_b32 v[96:97], v164 offset0:168 offset1:169
	ds_read2_b32 v[144:145], v164 offset0:170 offset1:171
	s_waitcnt lgkmcnt(3)
	v_pk_add_f32 v[192:193], v[2:3], v[78:79]
	s_waitcnt lgkmcnt(2)
	v_pk_add_f32 v[194:195], v[4:5], v[80:81]
	v_max3_f32 v2, v146, v192, v193
	v_max3_f32 v2, v2, v194, v195
	s_waitcnt lgkmcnt(1)
	v_pk_add_f32 v[196:197], v[6:7], v[96:97]
	s_waitcnt lgkmcnt(0)
	v_pk_add_f32 v[200:201], v[8:9], v[144:145]
	v_max3_f32 v6, v2, v196, v197
	ds_read2_b32 v[2:3], v164 offset0:176 offset1:177
	ds_read2_b32 v[4:5], v164 offset0:178 offset1:179
	v_max3_f32 v78, v6, v200, v201
	ds_read2_b32 v[6:7], v164 offset0:184 offset1:185
	ds_read2_b32 v[8:9], v164 offset0:186 offset1:187
	s_waitcnt lgkmcnt(3)
	v_pk_add_f32 v[202:203], v[10:11], v[2:3]
	s_waitcnt lgkmcnt(2)
	v_pk_add_f32 v[12:13], v[12:13], v[4:5]
	v_max3_f32 v2, v78, v202, v203
	v_max3_f32 v2, v2, v12, v13
	s_waitcnt lgkmcnt(1)
	v_pk_add_f32 v[14:15], v[14:15], v[6:7]
	s_waitcnt lgkmcnt(0)
	v_pk_add_f32 v[16:17], v[16:17], v[8:9]
	v_max3_f32 v2, v2, v14, v15
	v_max3_f32 v2, v2, v16, v17
	v_and_b32_e32 v4, 64, v191
	v_xor_b32_e32 v3, 32, v191
	v_add_u32_e32 v4, 64, v4
	v_cmp_lt_i32_e32 vcc, v3, v4
	s_nop 1
	v_cndmask_b32_e32 v3, v191, v3, vcc
	v_lshlrev_b32_e32 v11, 2, v3
	ds_bpermute_b32 v3, v11, v2
	s_waitcnt lgkmcnt(0)
	v_max_f32_e32 v3, v3, v3
	v_max_f32_e32 v10, v2, v3
	v_pk_add_f32 v[2:3], v[140:141], v[10:11] op_sel_hi:[1,0] neg_lo:[0,1] neg_hi:[0,1]
	v_pk_add_f32 v[78:79], v[142:143], v[10:11] op_sel_hi:[1,0] neg_lo:[0,1] neg_hi:[0,1]
	v_pk_add_f32 v[4:5], v[138:139], v[10:11] op_sel_hi:[1,0] neg_lo:[0,1] neg_hi:[0,1]
	v_exp_f32_e32 v2, v2
	v_exp_f32_e32 v3, v3
	v_exp_f32_e32 v166, v78
	v_exp_f32_e32 v167, v79
	v_pk_add_f32 v[78:79], v[88:89], v[10:11] op_sel_hi:[1,0] neg_lo:[0,1] neg_hi:[0,1]
	v_pk_add_f32 v[66:67], v[66:67], v[10:11] op_sel_hi:[1,0] neg_lo:[0,1] neg_hi:[0,1]
	v_exp_f32_e32 v4, v4
	v_exp_f32_e32 v5, v5
	v_pk_add_f32 v[6:7], v[84:85], v[10:11] op_sel_hi:[1,0] neg_lo:[0,1] neg_hi:[0,1]
	v_exp_f32_e32 v168, v78
	v_exp_f32_e32 v169, v79
	v_pk_add_f32 v[78:79], v[90:91], v[10:11] op_sel_hi:[1,0] neg_lo:[0,1] neg_hi:[0,1]
	v_exp_f32_e32 v152, v66
	v_exp_f32_e32 v153, v67
	v_pk_add_f32 v[66:67], v[94:95], v[10:11] op_sel_hi:[1,0] neg_lo:[0,1] neg_hi:[0,1]
	v_pk_add_f32 v[34:35], v[34:35], v[10:11] op_sel_hi:[1,0] neg_lo:[0,1] neg_hi:[0,1]
	v_pk_add_f32 v[12:13], v[12:13], v[10:11] op_sel_hi:[1,0] neg_lo:[0,1] neg_hi:[0,1]
	v_exp_f32_e32 v6, v6
	v_exp_f32_e32 v7, v7
	v_pk_add_f32 v[8:9], v[82:83], v[10:11] op_sel_hi:[1,0] neg_lo:[0,1] neg_hi:[0,1]
	v_exp_f32_e32 v170, v78
	v_exp_f32_e32 v171, v79
	v_pk_add_f32 v[78:79], v[86:87], v[10:11] op_sel_hi:[1,0] neg_lo:[0,1] neg_hi:[0,1]
	v_exp_f32_e32 v138, v66
	v_exp_f32_e32 v139, v67
	v_pk_add_f32 v[66:67], v[74:75], v[10:11] op_sel_hi:[1,0] neg_lo:[0,1] neg_hi:[0,1]
	v_exp_f32_e32 v74, v34
	v_exp_f32_e32 v75, v35
	v_pk_add_f32 v[34:35], v[36:37], v[10:11] op_sel_hi:[1,0] neg_lo:[0,1] neg_hi:[0,1]
	v_exp_f32_e32 v36, v12
	v_exp_f32_e32 v37, v13
; __device__ __forceinline__ void phase(LAS unsigned char* lds, int bx, int G, bf16_t* AB, bf16_t* dummy, const bf16_t* SKV, const float* cache_k, const float* cache_v, const float* sinks, const float* rel_bias) {
;     ...
;             const f32x2 nm = (f32x2){-mx, -mx};
;             f32x2 l2 = (f32x2){0.f, 0.f};
; #pragma unroll
;             for (int blk = 0; blk < 6; ++blk)
; #pragma unroll
;                 for (int q2 = 0; q2 < 8; ++q2) {
;                     const f32x2 a = (f32x2){sc[blk][2 * q2], sc[blk][2 * q2 + 1]} + nm;
;                     const f32x2 pe = (f32x2){__builtin_amdgcn_exp2f(a[0]), __builtin_amdgcn_exp2f(a[1])};
;                     sc[blk][2 * q2] = pe[0]; sc[blk][2 * q2 + 1] = pe[1]; l2 += pe;
;                 }
;             float l = l2[0] + l2[1];
;             l += __shfl_xor(l, 32);
;             l += __builtin_amdgcn_exp2f(sink - mx);
	v_pk_add_f32 v[12:13], v[14:15], v[10:11] op_sel_hi:[1,0] neg_lo:[0,1] neg_hi:[0,1]
	v_exp_f32_e32 v8, v8
	v_exp_f32_e32 v9, v9
	v_exp_f32_e32 v172, v78
	v_exp_f32_e32 v173, v79
	v_pk_add_f32 v[78:79], v[92:93], v[10:11] op_sel_hi:[1,0] neg_lo:[0,1] neg_hi:[0,1]
	v_exp_f32_e32 v140, v66
	v_exp_f32_e32 v141, v67
	v_pk_add_f32 v[66:67], v[76:77], v[10:11] op_sel_hi:[1,0] neg_lo:[0,1] neg_hi:[0,1]
	v_exp_f32_e32 v76, v34
	v_exp_f32_e32 v77, v35
	v_pk_add_f32 v[34:35], v[38:39], v[10:11] op_sel_hi:[1,0] neg_lo:[0,1] neg_hi:[0,1]
	v_exp_f32_e32 v38, v12
	v_exp_f32_e32 v39, v13
	v_pk_add_f32 v[12:13], v[16:17], v[10:11] op_sel_hi:[1,0] neg_lo:[0,1] neg_hi:[0,1]
	v_exp_f32_e32 v146, v78
	v_exp_f32_e32 v147, v79
	v_exp_f32_e32 v78, v34
	v_exp_f32_e32 v79, v35
	v_pk_add_f32 v[34:35], v[40:41], v[10:11] op_sel_hi:[1,0] neg_lo:[0,1] neg_hi:[0,1]
	v_exp_f32_e32 v40, v12
	v_exp_f32_e32 v41, v13
	v_pk_add_f32 v[12:13], v[2:3], 0 op_sel_hi:[1,0]
	v_pk_add_f32 v[68:69], v[68:69], v[10:11] op_sel_hi:[1,0] neg_lo:[0,1] neg_hi:[0,1]
	v_pk_add_f32 v[12:13], v[4:5], v[12:13]
	v_exp_f32_e32 v148, v68
	v_pk_add_f32 v[12:13], v[6:7], v[12:13]
	v_exp_f32_e32 v149, v69
	v_pk_add_f32 v[12:13], v[8:9], v[12:13]
	v_pk_add_f32 v[68:69], v[70:71], v[10:11] op_sel_hi:[1,0] neg_lo:[0,1] neg_hi:[0,1]
	v_pk_add_f32 v[12:13], v[166:167], v[12:13]
	v_exp_f32_e32 v150, v68
	v_pk_add_f32 v[12:13], v[168:169], v[12:13]
	v_exp_f32_e32 v151, v69
	v_pk_add_f32 v[12:13], v[170:171], v[12:13]
	v_exp_f32_e32 v142, v66
	v_pk_add_f32 v[12:13], v[172:173], v[12:13]
	v_exp_f32_e32 v143, v67
	v_pk_add_f32 v[12:13], v[146:147], v[12:13]
	v_pk_add_f32 v[66:67], v[72:73], v[10:11] op_sel_hi:[1,0] neg_lo:[0,1] neg_hi:[0,1]
	v_pk_add_f32 v[12:13], v[148:149], v[12:13]
	v_exp_f32_e32 v144, v66
	v_pk_add_f32 v[12:13], v[150:151], v[12:13]
	v_exp_f32_e32 v145, v67
	v_pk_add_f32 v[50:51], v[50:51], v[10:11] op_sel_hi:[1,0] neg_lo:[0,1] neg_hi:[0,1]
	v_pk_add_f32 v[12:13], v[152:153], v[12:13]
	v_exp_f32_e32 v90, v50
	v_exp_f32_e32 v91, v51
	v_pk_add_f32 v[50:51], v[52:53], v[10:11] op_sel_hi:[1,0] neg_lo:[0,1] neg_hi:[0,1]
	v_pk_add_f32 v[12:13], v[138:139], v[12:13]
	v_exp_f32_e32 v92, v50
	v_exp_f32_e32 v93, v51
	v_pk_add_f32 v[50:51], v[54:55], v[10:11] op_sel_hi:[1,0] neg_lo:[0,1] neg_hi:[0,1]
	v_pk_add_f32 v[12:13], v[140:141], v[12:13]
	v_exp_f32_e32 v94, v50
	v_exp_f32_e32 v95, v51
	v_pk_add_f32 v[50:51], v[56:57], v[10:11] op_sel_hi:[1,0] neg_lo:[0,1] neg_hi:[0,1]
	v_pk_add_f32 v[12:13], v[142:143], v[12:13]
	v_exp_f32_e32 v96, v50
	v_exp_f32_e32 v97, v51
	v_pk_add_f32 v[50:51], v[58:59], v[10:11] op_sel_hi:[1,0] neg_lo:[0,1] neg_hi:[0,1]
	v_pk_add_f32 v[12:13], v[144:145], v[12:13]
	v_exp_f32_e32 v82, v50
	v_exp_f32_e32 v83, v51
	v_pk_add_f32 v[50:51], v[60:61], v[10:11] op_sel_hi:[1,0] neg_lo:[0,1] neg_hi:[0,1]
	v_pk_add_f32 v[12:13], v[90:91], v[12:13]
	v_exp_f32_e32 v84, v50
	v_exp_f32_e32 v85, v51
	v_pk_add_f32 v[50:51], v[62:63], v[10:11] op_sel_hi:[1,0] neg_lo:[0,1] neg_hi:[0,1]
	v_pk_add_f32 v[12:13], v[92:93], v[12:13]
	v_exp_f32_e32 v86, v50
	v_exp_f32_e32 v87, v51
	v_pk_add_f32 v[50:51], v[64:65], v[10:11] op_sel_hi:[1,0] neg_lo:[0,1] neg_hi:[0,1]
	v_pk_add_f32 v[12:13], v[94:95], v[12:13]
	v_exp_f32_e32 v88, v50
	v_exp_f32_e32 v89, v51
	v_pk_add_f32 v[12:13], v[96:97], v[12:13]
	v_exp_f32_e32 v80, v34
	v_pk_add_f32 v[12:13], v[82:83], v[12:13]
	v_exp_f32_e32 v81, v35
	v_pk_add_f32 v[12:13], v[84:85], v[12:13]
	v_pk_add_f32 v[34:35], v[42:43], v[10:11] op_sel_hi:[1,0] neg_lo:[0,1] neg_hi:[0,1]
	v_pk_add_f32 v[12:13], v[86:87], v[12:13]
	v_exp_f32_e32 v66, v34
	v_pk_add_f32 v[12:13], v[88:89], v[12:13]
	v_exp_f32_e32 v67, v35
	v_pk_add_f32 v[34:35], v[44:45], v[10:11] op_sel_hi:[1,0] neg_lo:[0,1] neg_hi:[0,1]
	v_pk_add_f32 v[12:13], v[74:75], v[12:13]
	v_exp_f32_e32 v68, v34
	v_exp_f32_e32 v69, v35
	v_pk_add_f32 v[34:35], v[46:47], v[10:11] op_sel_hi:[1,0] neg_lo:[0,1] neg_hi:[0,1]
	v_pk_add_f32 v[12:13], v[76:77], v[12:13]
	v_exp_f32_e32 v70, v34
	v_exp_f32_e32 v71, v35
	v_pk_add_f32 v[34:35], v[48:49], v[10:11] op_sel_hi:[1,0] neg_lo:[0,1] neg_hi:[0,1]
	v_pk_add_f32 v[12:13], v[78:79], v[12:13]
	v_exp_f32_e32 v72, v34
	v_exp_f32_e32 v73, v35
	v_pk_add_f32 v[18:19], v[18:19], v[10:11] op_sel_hi:[1,0] neg_lo:[0,1] neg_hi:[0,1]
	v_pk_add_f32 v[12:13], v[80:81], v[12:13]
	v_exp_f32_e32 v58, v18
	v_exp_f32_e32 v59, v19
	v_pk_add_f32 v[18:19], v[20:21], v[10:11] op_sel_hi:[1,0] neg_lo:[0,1] neg_hi:[0,1]
	v_pk_add_f32 v[12:13], v[66:67], v[12:13]
	v_exp_f32_e32 v60, v18
	v_exp_f32_e32 v61, v19
	v_pk_add_f32 v[18:19], v[22:23], v[10:11] op_sel_hi:[1,0] neg_lo:[0,1] neg_hi:[0,1]
	v_pk_add_f32 v[12:13], v[68:69], v[12:13]
	v_exp_f32_e32 v62, v18
	v_exp_f32_e32 v63, v19
	v_pk_add_f32 v[18:19], v[24:25], v[10:11] op_sel_hi:[1,0] neg_lo:[0,1] neg_hi:[0,1]
	v_pk_add_f32 v[12:13], v[70:71], v[12:13]
	v_exp_f32_e32 v64, v18
	v_exp_f32_e32 v65, v19
	v_pk_add_f32 v[18:19], v[26:27], v[10:11] op_sel_hi:[1,0] neg_lo:[0,1] neg_hi:[0,1]
	v_pk_add_f32 v[12:13], v[72:73], v[12:13]
	v_exp_f32_e32 v50, v18
	v_exp_f32_e32 v51, v19
	v_pk_add_f32 v[18:19], v[28:29], v[10:11] op_sel_hi:[1,0] neg_lo:[0,1] neg_hi:[0,1]
	v_pk_add_f32 v[12:13], v[58:59], v[12:13]
	v_exp_f32_e32 v52, v18
	v_exp_f32_e32 v53, v19
	v_pk_add_f32 v[18:19], v[30:31], v[10:11] op_sel_hi:[1,0] neg_lo:[0,1] neg_hi:[0,1]
	v_pk_add_f32 v[12:13], v[60:61], v[12:13]
	v_exp_f32_e32 v54, v18
	v_exp_f32_e32 v55, v19
	v_pk_add_f32 v[18:19], v[32:33], v[10:11] op_sel_hi:[1,0] neg_lo:[0,1] neg_hi:[0,1]
	v_pk_add_f32 v[12:13], v[62:63], v[12:13]
	v_exp_f32_e32 v56, v18
	v_exp_f32_e32 v57, v19
	v_pk_add_f32 v[18:19], v[192:193], v[10:11] op_sel_hi:[1,0] neg_lo:[0,1] neg_hi:[0,1]
	v_pk_add_f32 v[12:13], v[64:65], v[12:13]
	v_exp_f32_e32 v42, v18
	v_exp_f32_e32 v43, v19
	v_pk_add_f32 v[18:19], v[194:195], v[10:11] op_sel_hi:[1,0] neg_lo:[0,1] neg_hi:[0,1]
	v_pk_add_f32 v[12:13], v[50:51], v[12:13]
	v_exp_f32_e32 v44, v18
	v_exp_f32_e32 v45, v19
	v_pk_add_f32 v[18:19], v[196:197], v[10:11] op_sel_hi:[1,0] neg_lo:[0,1] neg_hi:[0,1]
	v_pk_add_f32 v[12:13], v[52:53], v[12:13]
	v_exp_f32_e32 v46, v18
	v_exp_f32_e32 v47, v19
	v_pk_add_f32 v[18:19], v[200:201], v[10:11] op_sel_hi:[1,0] neg_lo:[0,1] neg_hi:[0,1]
	v_pk_add_f32 v[12:13], v[54:55], v[12:13]
	v_exp_f32_e32 v48, v18
	v_exp_f32_e32 v49, v19
	v_pk_add_f32 v[18:19], v[202:203], v[10:11] op_sel_hi:[1,0] neg_lo:[0,1] neg_hi:[0,1]
	v_pk_add_f32 v[12:13], v[56:57], v[12:13]
	v_exp_f32_e32 v34, v18
	v_exp_f32_e32 v35, v19
	v_pk_add_f32 v[12:13], v[42:43], v[12:13]
	v_sub_f32_e32 v10, v161, v10
	v_pk_add_f32 v[12:13], v[44:45], v[12:13]
	v_exp_f32_e32 v10, v10
	v_pk_add_f32 v[12:13], v[46:47], v[12:13]
	v_mov_b32_e32 v161, v186
	v_pk_add_f32 v[12:13], v[48:49], v[12:13]
	s_nop 0
	v_pk_add_f32 v[12:13], v[34:35], v[12:13]
	s_nop 0
	v_pk_add_f32 v[12:13], v[36:37], v[12:13]
	s_nop 0
	v_pk_add_f32 v[12:13], v[38:39], v[12:13]
	s_nop 0
	v_pk_add_f32 v[12:13], v[40:41], v[12:13]
	s_nop 0
	v_add_f32_e32 v12, v12, v13
	ds_bpermute_b32 v11, v11, v12
	s_waitcnt lgkmcnt(0)
; #define LAS __attribute__((address_space(3)))
; __device__ __forceinline__ unsigned cvtpk(float lo, float hi) { f32x2_t v = {lo, hi}; bf16x2_t b = __builtin_convertvector(v, bf16x2_t); return __builtin_bit_cast(unsigned, b); }
; template <class T> __device__ __forceinline__ LAS T* opq_after(LAS T* p, float dep) { unsigned a = __builtin_bit_cast(unsigned, p); asm volatile("" : "+v"(a) : "v"(dep)); return __builtin_bit_cast(LAS T*, a); }
; #define MFMA32(a, b, c) __builtin_amdgcn_mfma_f32_32x32x16_bf16((a), (b), (c), 0, 0, 0)
; __device__ __forceinline__ void phase(LAS unsigned char* lds, int bx, int G, bf16_t* AB, bf16_t* dummy, const bf16_t* SKV, const float* cache_k, const float* cache_v, const float* sinks, const float* rel_bias) {
;     ...
;             float l = l2[0] + l2[1];
;             l += __shfl_xor(l, 32);
;             l += __builtin_amdgcn_exp2f(sink - mx);
;             const float inv = 1.0f / l;
;             f32x16 o[2];
; #pragma unroll
;             for (int d = 0; d < 2; ++d) o[d] = (f32x16){0.f, 0.f, 0.f, 0.f, 0.f, 0.f, 0.f, 0.f, 0.f, 0.f, 0.f, 0.f, 0.f, 0.f, 0.f, 0.f};
;             const LAS bf16_t* vrp = opq_after(Vs + (4 * h + ((lane & 15) >> 2)) * VSS + 16 * ((lane >> 4) & 1) + 4 * (lane & 3), inv);
; #pragma unroll
;             for (int blk = 0; blk < 6; ++blk) {
; #pragma unroll
;                 for (int s2 = 0; s2 < 2; ++s2) {
;                     u32x4 pw; pw.x = cvtpk(sc[blk][8 * s2 + 0] * inv, sc[blk][8 * s2 + 1] * inv); pw.y = cvtpk(sc[blk][8 * s2 + 2] * inv, sc[blk][8 * s2 + 3] * inv);
;                     pw.z = cvtpk(sc[blk][8 * s2 + 4] * inv, sc[blk][8 * s2 + 5] * inv); pw.w = cvtpk(sc[blk][8 * s2 + 6] * inv, sc[blk][8 * s2 + 7] * inv);
;                     const bf16x8 pa = __builtin_bit_cast(bf16x8, pw);
; #pragma unroll
;                     for (int d = 0; d < 2; ++d) {
;                         const LAS bf16_t* vp = vrp + (32 * blk + 16 * s2) * VSS + 32 * d;
;                         const s16x4 lo = tr16(vp), hi = tr16(vp + 8 * VSS);
;                         const bf16x8 vb = __builtin_shufflevector(lo, hi, 0, 1, 2, 3, 4, 5, 6, 7);
;                         o[d] = MFMA32(pa, vb, o[d]);
;                     }
;                 }
;                 __builtin_amdgcn_sched_barrier(0);
;             }
	v_add_f32_e32 v11, v12, v11
	v_add_f32_e32 v10, v10, v11
	v_div_scale_f32 v11, s[4:5], v10, v10, 1.0
	v_rcp_f32_e32 v12, v11
	s_nop 0
	v_fma_f32 v13, -v11, v12, 1.0
	v_fmac_f32_e32 v12, v13, v12
	v_div_scale_f32 v13, vcc, 1.0, v10, 1.0
	v_mul_f32_e32 v14, v13, v12
	v_fma_f32 v15, -v11, v14, v13
	v_fmac_f32_e32 v14, v15, v12
	v_fma_f32 v11, -v11, v14, v13
	v_div_fmas_f32 v11, v11, v12, v14
	v_div_fixup_f32 v164, v11, v10, 1.0
	v_pk_mul_f32 v[2:3], v[2:3], v[164:165] op_sel_hi:[1,0]
	v_pk_mul_f32 v[4:5], v[4:5], v[164:165] op_sel_hi:[1,0]
	v_cvt_pk_bf16_f32 v2, v2, v3
	v_cvt_pk_bf16_f32 v3, v4, v5
	v_pk_mul_f32 v[4:5], v[6:7], v[164:165] op_sel_hi:[1,0]
	v_pk_mul_f32 v[6:7], v[8:9], v[164:165] op_sel_hi:[1,0]
	v_cvt_pk_bf16_f32 v4, v4, v5
	v_cvt_pk_bf16_f32 v5, v6, v7
	ds_read_b64_tr_b16 v[6:7], v161
	ds_read_b64_tr_b16 v[8:9], v161 offset:1536
	ds_read_b64_tr_b16 v[12:13], v161 offset:1600
	ds_read_b64_tr_b16 v[10:11], v161 offset:64
	s_waitcnt lgkmcnt(2)
	v_mfma_f32_32x32x16_bf16 v[18:33], v[2:5], v[6:9], 0
	v_mul_f32_e64 v166, v166, v164
	v_mul_f32_e64 v167, v167, v164
	v_mul_f32_e64 v168, v168, v164
	v_mul_f32_e64 v169, v169, v164
	v_cvt_pk_bf16_f32 v166, v166, v167
	v_cvt_pk_bf16_f32 v167, v168, v169
	v_pk_mul_f32 v[168:169], v[170:171], v[164:165] op_sel_hi:[1,0]
	v_pk_mul_f32 v[170:171], v[172:173], v[164:165] op_sel_hi:[1,0]
	v_cvt_pk_bf16_f32 v168, v168, v169
	s_waitcnt lgkmcnt(0)
	v_mfma_f32_32x32x16_bf16 v[2:17], v[2:5], v[10:13], 0
	v_cvt_pk_bf16_f32 v169, v170, v171
	ds_read_b64_tr_b16 v[170:171], v161 offset:3072
	ds_read_b64_tr_b16 v[172:173], v161 offset:4608
	ds_read_b64_tr_b16 v[194:195], v161 offset:4672
	ds_read_b64_tr_b16 v[192:193], v161 offset:3136
	s_waitcnt lgkmcnt(2)
	v_mfma_f32_32x32x16_bf16 v[18:33], v[166:169], v[170:173], v[18:33]
	s_waitcnt lgkmcnt(0)
	v_mfma_f32_32x32x16_bf16 v[2:17], v[166:169], v[192:195], v[2:17]
	v_mul_f32_e64 v146, v146, v164
	v_mul_f32_e64 v147, v147, v164
	v_mul_f32_e64 v148, v148, v164
	v_mul_f32_e64 v149, v149, v164
	v_cvt_pk_bf16_f32 v146, v146, v147
	v_cvt_pk_bf16_f32 v147, v148, v149
	v_pk_mul_f32 v[148:149], v[150:151], v[164:165] op_sel_hi:[1,0]
	v_pk_mul_f32 v[150:151], v[152:153], v[164:165] op_sel_hi:[1,0]
	v_cvt_pk_bf16_f32 v148, v148, v149
	v_cvt_pk_bf16_f32 v149, v150, v151
	ds_read_b64_tr_b16 v[150:151], v161 offset:6144
	ds_read_b64_tr_b16 v[152:153], v161 offset:7680
	ds_read_b64_tr_b16 v[168:169], v161 offset:7744
	ds_read_b64_tr_b16 v[166:167], v161 offset:6208
	s_waitcnt lgkmcnt(2)
	v_mfma_f32_32x32x16_bf16 v[18:33], v[146:149], v[150:153], v[18:33]
	v_mul_f32_e64 v138, v138, v164
	v_mul_f32_e64 v139, v139, v164
	v_mul_f32_e64 v140, v140, v164
	v_mul_f32_e64 v141, v141, v164
	v_cvt_pk_bf16_f32 v138, v138, v139
	v_cvt_pk_bf16_f32 v139, v140, v141
	v_pk_mul_f32 v[140:141], v[142:143], v[164:165] op_sel_hi:[1,0]
	v_pk_mul_f32 v[142:143], v[144:145], v[164:165] op_sel_hi:[1,0]
	v_cvt_pk_bf16_f32 v140, v140, v141
	s_waitcnt lgkmcnt(0)
	v_mfma_f32_32x32x16_bf16 v[2:17], v[146:149], v[166:169], v[2:17]
	v_cvt_pk_bf16_f32 v141, v142, v143
	ds_read_b64_tr_b16 v[142:143], v161 offset:9216
	ds_read_b64_tr_b16 v[144:145], v161 offset:10752
	ds_read_b64_tr_b16 v[148:149], v161 offset:10816
	ds_read_b64_tr_b16 v[146:147], v161 offset:9280
	s_waitcnt lgkmcnt(2)
	v_mfma_f32_32x32x16_bf16 v[18:33], v[138:141], v[142:145], v[18:33]
	s_waitcnt lgkmcnt(0)
	v_mfma_f32_32x32x16_bf16 v[2:17], v[138:141], v[146:149], v[2:17]
	v_mul_f32_e64 v90, v90, v164
	v_mul_f32_e64 v91, v91, v164
	v_mul_f32_e64 v92, v92, v164
	v_mul_f32_e64 v93, v93, v164
	v_cvt_pk_bf16_f32 v90, v90, v91
	v_cvt_pk_bf16_f32 v91, v92, v93
	v_pk_mul_f32 v[92:93], v[94:95], v[164:165] op_sel_hi:[1,0]
	v_pk_mul_f32 v[94:95], v[96:97], v[164:165] op_sel_hi:[1,0]
	v_cvt_pk_bf16_f32 v92, v92, v93
	v_cvt_pk_bf16_f32 v93, v94, v95
	ds_read_b64_tr_b16 v[94:95], v161 offset:12288
	ds_read_b64_tr_b16 v[96:97], v161 offset:13824
	ds_read_b64_tr_b16 v[140:141], v161 offset:13888
	ds_read_b64_tr_b16 v[138:139], v161 offset:12352
	s_waitcnt lgkmcnt(2)
	v_mfma_f32_32x32x16_bf16 v[18:33], v[90:93], v[94:97], v[18:33]
	v_mul_f32_e64 v82, v82, v164
	v_mul_f32_e64 v83, v83, v164
	v_mul_f32_e64 v84, v84, v164
	v_mul_f32_e64 v85, v85, v164
	v_cvt_pk_bf16_f32 v82, v82, v83
	v_cvt_pk_bf16_f32 v83, v84, v85
	v_pk_mul_f32 v[84:85], v[86:87], v[164:165] op_sel_hi:[1,0]
	v_pk_mul_f32 v[86:87], v[88:89], v[164:165] op_sel_hi:[1,0]
	v_cvt_pk_bf16_f32 v84, v84, v85
	s_waitcnt lgkmcnt(0)
	v_mfma_f32_32x32x16_bf16 v[2:17], v[90:93], v[138:141], v[2:17]
	v_cvt_pk_bf16_f32 v85, v86, v87
	ds_read_b64_tr_b16 v[86:87], v161 offset:15360
	ds_read_b64_tr_b16 v[88:89], v161 offset:16896
	ds_read_b64_tr_b16 v[92:93], v161 offset:16960
	ds_read_b64_tr_b16 v[90:91], v161 offset:15424
	s_waitcnt lgkmcnt(2)
; #define LAS __attribute__((address_space(3)))
; __device__ __forceinline__ unsigned cvtpk(float lo, float hi) { f32x2_t v = {lo, hi}; bf16x2_t b = __builtin_convertvector(v, bf16x2_t); return __builtin_bit_cast(unsigned, b); }
; #define MFMA32(a, b, c) __builtin_amdgcn_mfma_f32_32x32x16_bf16((a), (b), (c), 0, 0, 0)
; __device__ __forceinline__ s16x4 tr16(const LAS bf16_t* p) { return __builtin_bit_cast(s16x4, __builtin_amdgcn_ds_read_tr16_b64_v4i16((LAS v4i16_t*)p)); }
; __device__ __forceinline__ s16x4 tr16(const LAS bf16_t* p) { return __builtin_bit_cast(s16x4, __builtin_amdgcn_ds_read_tr16_b64_v4i16((LAS v4i16_t*)p)); }
; __device__ __forceinline__ void phase(LAS unsigned char* lds, int bx, int G, bf16_t* AB, bf16_t* dummy, const bf16_t* SKV, const float* cache_k, const float* cache_v, const float* sinks, const float* rel_bias) {
;     ...
; #pragma unroll
;             for (int blk = 0; blk < 6; ++blk) {
; #pragma unroll
;                 for (int s2 = 0; s2 < 2; ++s2) {
;                     u32x4 pw; pw.x = cvtpk(sc[blk][8 * s2 + 0] * inv, sc[blk][8 * s2 + 1] * inv); pw.y = cvtpk(sc[blk][8 * s2 + 2] * inv, sc[blk][8 * s2 + 3] * inv);
;                     pw.z = cvtpk(sc[blk][8 * s2 + 4] * inv, sc[blk][8 * s2 + 5] * inv); pw.w = cvtpk(sc[blk][8 * s2 + 6] * inv, sc[blk][8 * s2 + 7] * inv);
;                     const bf16x8 pa = __builtin_bit_cast(bf16x8, pw);
; #pragma unroll
;                     for (int d = 0; d < 2; ++d) {
;                         const LAS bf16_t* vp = vrp + (32 * blk + 16 * s2) * VSS + 32 * d;
;                         const s16x4 lo = tr16(vp), hi = tr16(vp + 8 * VSS);
;                         const bf16x8 vb = __builtin_shufflevector(lo, hi, 0, 1, 2, 3, 4, 5, 6, 7);
;                         o[d] = MFMA32(pa, vb, o[d]);
;                     }
;                 }
;                 __builtin_amdgcn_sched_barrier(0);
;             }
;             {
;                 const size_t orow0 = samp ? (size_t)(MP + b * 16) : (size_t)(b * SEQ + 64 * c + 32 * (w & 1));
	v_mfma_f32_32x32x16_bf16 v[18:33], v[82:85], v[86:89], v[18:33]
	s_waitcnt lgkmcnt(0)
	v_mfma_f32_32x32x16_bf16 v[2:17], v[82:85], v[90:93], v[2:17]
	v_mul_f32_e64 v74, v74, v164
	v_mul_f32_e64 v75, v75, v164
	v_mul_f32_e64 v76, v76, v164
	v_mul_f32_e64 v77, v77, v164
	v_cvt_pk_bf16_f32 v74, v74, v75
	v_cvt_pk_bf16_f32 v75, v76, v77
	v_pk_mul_f32 v[76:77], v[78:79], v[164:165] op_sel_hi:[1,0]
	v_pk_mul_f32 v[78:79], v[80:81], v[164:165] op_sel_hi:[1,0]
	v_cvt_pk_bf16_f32 v76, v76, v77
	v_cvt_pk_bf16_f32 v77, v78, v79
	ds_read_b64_tr_b16 v[78:79], v161 offset:18432
	ds_read_b64_tr_b16 v[80:81], v161 offset:19968
	ds_read_b64_tr_b16 v[84:85], v161 offset:20032
	ds_read_b64_tr_b16 v[82:83], v161 offset:18496
	s_waitcnt lgkmcnt(2)
	v_mfma_f32_32x32x16_bf16 v[18:33], v[74:77], v[78:81], v[18:33]
	v_mul_f32_e64 v66, v66, v164
	v_mul_f32_e64 v67, v67, v164
	v_mul_f32_e64 v68, v68, v164
	v_mul_f32_e64 v69, v69, v164
	v_cvt_pk_bf16_f32 v66, v66, v67
	v_cvt_pk_bf16_f32 v67, v68, v69
	v_pk_mul_f32 v[68:69], v[70:71], v[164:165] op_sel_hi:[1,0]
	v_pk_mul_f32 v[70:71], v[72:73], v[164:165] op_sel_hi:[1,0]
	v_cvt_pk_bf16_f32 v68, v68, v69
	s_waitcnt lgkmcnt(0)
	v_mfma_f32_32x32x16_bf16 v[2:17], v[74:77], v[82:85], v[2:17]
	v_cvt_pk_bf16_f32 v69, v70, v71
	ds_read_b64_tr_b16 v[70:71], v161 offset:21504
	ds_read_b64_tr_b16 v[72:73], v161 offset:23040
	ds_read_b64_tr_b16 v[76:77], v161 offset:23104
	ds_read_b64_tr_b16 v[74:75], v161 offset:21568
	s_waitcnt lgkmcnt(2)
	v_mfma_f32_32x32x16_bf16 v[18:33], v[66:69], v[70:73], v[18:33]
	s_waitcnt lgkmcnt(0)
	v_mfma_f32_32x32x16_bf16 v[2:17], v[66:69], v[74:77], v[2:17]
	v_mul_f32_e64 v58, v58, v164
	v_mul_f32_e64 v59, v59, v164
	v_mul_f32_e64 v60, v60, v164
	v_mul_f32_e64 v61, v61, v164
	v_cvt_pk_bf16_f32 v58, v58, v59
	v_cvt_pk_bf16_f32 v59, v60, v61
	v_pk_mul_f32 v[60:61], v[62:63], v[164:165] op_sel_hi:[1,0]
	v_pk_mul_f32 v[62:63], v[64:65], v[164:165] op_sel_hi:[1,0]
	v_cvt_pk_bf16_f32 v60, v60, v61
	v_cvt_pk_bf16_f32 v61, v62, v63
	ds_read_b64_tr_b16 v[62:63], v161 offset:24576
	ds_read_b64_tr_b16 v[64:65], v161 offset:26112
	ds_read_b64_tr_b16 v[68:69], v161 offset:26176
	ds_read_b64_tr_b16 v[66:67], v161 offset:24640
	s_waitcnt lgkmcnt(2)
	v_mfma_f32_32x32x16_bf16 v[18:33], v[58:61], v[62:65], v[18:33]
	v_mul_f32_e64 v50, v50, v164
	v_mul_f32_e64 v51, v51, v164
	v_mul_f32_e64 v52, v52, v164
	v_mul_f32_e64 v53, v53, v164
	v_cvt_pk_bf16_f32 v50, v50, v51
	v_cvt_pk_bf16_f32 v51, v52, v53
	v_pk_mul_f32 v[52:53], v[54:55], v[164:165] op_sel_hi:[1,0]
	v_pk_mul_f32 v[54:55], v[56:57], v[164:165] op_sel_hi:[1,0]
	v_cvt_pk_bf16_f32 v52, v52, v53
	s_waitcnt lgkmcnt(0)
	v_mfma_f32_32x32x16_bf16 v[2:17], v[58:61], v[66:69], v[2:17]
	v_cvt_pk_bf16_f32 v53, v54, v55
	ds_read_b64_tr_b16 v[54:55], v161 offset:27648
	ds_read_b64_tr_b16 v[56:57], v161 offset:29184
	ds_read_b64_tr_b16 v[60:61], v161 offset:29248
	ds_read_b64_tr_b16 v[58:59], v161 offset:27712
	s_waitcnt lgkmcnt(2)
	v_mfma_f32_32x32x16_bf16 v[18:33], v[50:53], v[54:57], v[18:33]
	s_waitcnt lgkmcnt(0)
	v_mfma_f32_32x32x16_bf16 v[2:17], v[50:53], v[58:61], v[2:17]
	v_mul_f32_e64 v42, v42, v164
	v_mul_f32_e64 v43, v43, v164
	v_mul_f32_e64 v44, v44, v164
	v_mul_f32_e64 v45, v45, v164
	v_cvt_pk_bf16_f32 v42, v42, v43
	v_cvt_pk_bf16_f32 v43, v44, v45
	v_pk_mul_f32 v[44:45], v[46:47], v[164:165] op_sel_hi:[1,0]
	v_pk_mul_f32 v[46:47], v[48:49], v[164:165] op_sel_hi:[1,0]
	v_cvt_pk_bf16_f32 v44, v44, v45
	v_cvt_pk_bf16_f32 v45, v46, v47
	ds_read_b64_tr_b16 v[46:47], v161 offset:30720
	ds_read_b64_tr_b16 v[48:49], v161 offset:32256
	ds_read_b64_tr_b16 v[52:53], v161 offset:32320
	ds_read_b64_tr_b16 v[50:51], v161 offset:30784
	s_waitcnt lgkmcnt(2)
	v_mfma_f32_32x32x16_bf16 v[18:33], v[42:45], v[46:49], v[18:33]
	v_mul_f32_e64 v34, v34, v164
	v_mul_f32_e64 v35, v35, v164
	v_mul_f32_e64 v36, v36, v164
	v_mul_f32_e64 v37, v37, v164
	v_cvt_pk_bf16_f32 v34, v34, v35
	v_cvt_pk_bf16_f32 v35, v36, v37
	v_pk_mul_f32 v[36:37], v[38:39], v[164:165] op_sel_hi:[1,0]
	v_pk_mul_f32 v[38:39], v[40:41], v[164:165] op_sel_hi:[1,0]
	v_cvt_pk_bf16_f32 v36, v36, v37
	s_waitcnt lgkmcnt(0)
	v_mfma_f32_32x32x16_bf16 v[2:17], v[42:45], v[50:53], v[2:17]
	v_cvt_pk_bf16_f32 v37, v38, v39
	ds_read_b64_tr_b16 v[38:39], v161 offset:33792
	ds_read_b64_tr_b16 v[40:41], v161 offset:35328
	ds_read_b64_tr_b16 v[44:45], v161 offset:35392
	ds_read_b64_tr_b16 v[42:43], v161 offset:33856
	s_waitcnt lgkmcnt(2)
	v_mfma_f32_32x32x16_bf16 v[18:33], v[34:37], v[38:41], v[18:33]
	s_waitcnt lgkmcnt(0)
	v_mfma_f32_32x32x16_bf16 v[2:17], v[34:37], v[42:45], v[2:17]
	s_mov_b64 s[4:5], -1
	s_and_b64 vcc, exec, s[24:25]
	s_cbranch_vccz .LBB0_1190
	s_lshl_b32 s4, s30, 12
	s_or_b32 s4, s4, s33
	s_or_b32 s34, s31, s4
	s_mov_b64 s[4:5], 0
